# HGRN scan chunk: LDS reads of the three MFMA steps issued ahead (ring of spare VGPRs, counted lgkmcnt), decay factors and KLt fragments prefetched, V fragments no longer re-read
# baseline (speedup 1.0000x reference)
.LBB0_376:
	v_add_u32_e32 v140, s36, v111
	v_ashrrev_i32_e32 v141, 31, v140
	v_lshlrev_b64 v[52:53], 10, v[140:141]
	v_lshl_add_u64 v[52:53], v[136:137], 0, v[52:53]
	global_load_dwordx2 v[128:129], v[52:53], off
	global_load_dwordx2 v[138:139], v[52:53], off offset:32
	global_load_dwordx2 v[134:135], v[52:53], off offset:64
	global_load_dwordx2 v[132:133], v[52:53], off offset:96
	v_cvt_pk_bf16_f32 v52, v8, v9
	v_cvt_pk_bf16_f32 v53, v10, v11
	ds_write_b64 v119, v[52:53]
	v_cvt_pk_bf16_f32 v52, v16, v17
	v_cvt_pk_bf16_f32 v53, v18, v19
	ds_write_b64 v119, v[52:53] offset:4352
	v_cvt_pk_bf16_f32 v52, v12, v13
	v_cvt_pk_bf16_f32 v53, v14, v15
	ds_write_b64 v119, v[52:53] offset:8704
	v_cvt_pk_bf16_f32 v52, v20, v21
	v_cvt_pk_bf16_f32 v53, v22, v23
	ds_write_b64 v119, v[52:53] offset:13056
	v_cvt_pk_bf16_f32 v52, v36, v37
	v_cvt_pk_bf16_f32 v53, v38, v39
	ds_write_b64 v119, v[52:53] offset:32
	v_cvt_pk_bf16_f32 v52, v40, v41
	v_cvt_pk_bf16_f32 v53, v42, v43
	ds_write_b64 v119, v[52:53] offset:4384
	v_cvt_pk_bf16_f32 v52, v44, v45
	v_cvt_pk_bf16_f32 v53, v46, v47
	ds_write_b64 v119, v[52:53] offset:8736
	v_cvt_pk_bf16_f32 v52, v48, v49
	v_cvt_pk_bf16_f32 v53, v50, v51
	ds_write_b64 v119, v[52:53] offset:13088
	s_waitcnt lgkmcnt(0)
	s_barrier
	ds_read_b128 v[60:63], v121 offset:17408
	ds_read_b128 v[64:67], v123
	ds_read_b128 v[152:155], v123 offset:4352
	ds_read_b128 v[156:159], v121 offset:17472
	ds_read_b128 v[224:227], v123 offset:64
	ds_read_b128 v[228:231], v123 offset:4416
	ds_read_b128 v[232:235], v121 offset:17536
	ds_read_b128 v[236:239], v123 offset:128
	ds_read_b128 v[240:243], v123 offset:4480
	ds_read_b128 v[244:247], v121 offset:17600
	ds_read_b128 v[248:251], v123 offset:192
	s_waitcnt lgkmcnt(9)
	v_mfma_f32_16x16x32_bf16 v[56:59], v[60:63], v[64:67], 0
	s_waitcnt lgkmcnt(8)
	v_mfma_f32_16x16x32_bf16 v[52:55], v[60:63], v[152:155], 0
	ds_read_b128 v[60:63], v123 offset:4544
	s_waitcnt lgkmcnt(7)
	v_mfma_f32_16x16x32_bf16 v[56:59], v[156:159], v[224:227], v[56:59]
	s_waitcnt lgkmcnt(6)
	v_mfma_f32_16x16x32_bf16 v[52:55], v[156:159], v[228:231], v[52:55]
	s_waitcnt lgkmcnt(4)
	v_mfma_f32_16x16x32_bf16 v[56:59], v[232:235], v[236:239], v[56:59]
	s_waitcnt lgkmcnt(3)
	v_mfma_f32_16x16x32_bf16 v[52:55], v[232:235], v[240:243], v[52:55]
	s_waitcnt lgkmcnt(1)
	v_mfma_f32_16x16x32_bf16 v[56:59], v[244:247], v[248:251], v[56:59]
	s_waitcnt lgkmcnt(0)
	v_mfma_f32_16x16x32_bf16 v[52:55], v[244:247], v[60:63], v[52:55]
	s_nop 5
	v_cndmask_b32_e64 v56, v56, 0, s[18:19]
	v_cndmask_b32_e64 v57, 0, v57, s[20:21]
	v_cndmask_b32_e64 v58, v58, 0, s[22:23]
	v_cndmask_b32_e64 v52, v52, 0, s[26:27]
	v_cndmask_b32_e64 v53, 0, v53, s[28:29]
	v_cndmask_b32_e64 v59, v59, 0, s[24:25]
	v_cvt_pk_bf16_f32 v56, v56, v57
	v_cvt_pk_bf16_f32 v57, v58, v59
	ds_write_b64 v125, v[56:57]
	v_cndmask_b32_e64 v54, v54, 0, s[30:31]
	v_cndmask_b32_e64 v55, v55, 0, s[34:35]
	v_cvt_pk_bf16_f32 v52, v52, v53
	v_cvt_pk_bf16_f32 v53, v54, v55
	ds_write_b64 v125, v[52:53] offset:2304
	s_waitcnt lgkmcnt(0)
	s_barrier
	ds_read_b128 v[68:71], v121 offset:34816
	ds_read_b128 v[72:75], v127
	ds_read_b128 v[76:79], v127 offset:4352
	ds_read_b128 v[80:83], v127 offset:8704
	ds_read_b128 v[84:87], v127 offset:13056
	ds_read_b128 v[88:91], v121 offset:34880
	ds_read_b128 v[92:95], v127 offset:64
	ds_read_b128 v[96:99], v127 offset:4416
	ds_read_b128 v[152:155], v127 offset:8768
	ds_read_b128 v[156:159], v127 offset:13120
	ds_read_b128 v[224:227], v121 offset:34944
	ds_read_b128 v[228:231], v127 offset:128
	ds_read_b128 v[232:235], v127 offset:4480
	ds_read_b128 v[236:239], v127 offset:8832
	ds_read_b128 v[240:243], v127 offset:13184
	s_waitcnt lgkmcnt(13)
	v_mfma_f32_16x16x32_bf16 v[56:59], v[72:75], v[68:71], 0
	s_waitcnt lgkmcnt(12)
	v_mfma_f32_16x16x32_bf16 v[60:63], v[76:79], v[68:71], 0
	s_waitcnt lgkmcnt(11)
	v_mfma_f32_16x16x32_bf16 v[64:67], v[80:83], v[68:71], 0
	s_waitcnt lgkmcnt(10)
	v_mfma_f32_16x16x32_bf16 v[52:55], v[84:87], v[68:71], 0
	ds_read_b128 v[244:247], v121 offset:35008
	ds_read_b128 v[248:251], v127 offset:192
	ds_read_b128 v[72:75], v127 offset:4544
	ds_read_b128 v[76:79], v127 offset:8896
	ds_read_b128 v[80:83], v127 offset:13248
	s_waitcnt lgkmcnt(13)
	v_mfma_f32_16x16x32_bf16 v[56:59], v[92:95], v[88:91], v[56:59]
	s_waitcnt lgkmcnt(12)
	v_mfma_f32_16x16x32_bf16 v[60:63], v[96:99], v[88:91], v[60:63]
	s_waitcnt lgkmcnt(11)
	v_mfma_f32_16x16x32_bf16 v[64:67], v[152:155], v[88:91], v[64:67]
	s_waitcnt lgkmcnt(10)
	v_mfma_f32_16x16x32_bf16 v[52:55], v[156:159], v[88:91], v[52:55]
	s_waitcnt lgkmcnt(8)
	v_mfma_f32_16x16x32_bf16 v[56:59], v[228:231], v[224:227], v[56:59]
	s_waitcnt lgkmcnt(7)
	v_mfma_f32_16x16x32_bf16 v[60:63], v[232:235], v[224:227], v[60:63]
	s_waitcnt lgkmcnt(6)
	v_mfma_f32_16x16x32_bf16 v[64:67], v[236:239], v[224:227], v[64:67]
	s_waitcnt lgkmcnt(5)
	v_mfma_f32_16x16x32_bf16 v[52:55], v[240:243], v[224:227], v[52:55]
	ds_read_b128 v[224:227], v195
	ds_read_b128 v[228:231], v195 offset:64
	ds_read_b128 v[232:235], v196 offset:52224
	ds_read_b128 v[236:239], v196 offset:54528
	ds_read_b128 v[240:243], v196 offset:52288
	ds_read_b128 v[152:155], v196 offset:54592
	s_waitcnt lgkmcnt(9)
	v_mfma_f32_16x16x32_bf16 v[56:59], v[248:251], v[244:247], v[56:59]
	s_waitcnt lgkmcnt(8)
	v_mfma_f32_16x16x32_bf16 v[60:63], v[72:75], v[244:247], v[60:63]
	s_waitcnt lgkmcnt(7)
	v_mfma_f32_16x16x32_bf16 v[64:67], v[76:79], v[244:247], v[64:67]
	s_waitcnt lgkmcnt(6)
	v_mfma_f32_16x16x32_bf16 v[52:55], v[80:83], v[244:247], v[52:55]
	ds_read_b128 v[68:71], v194
	ds_read_b128 v[88:91], v197
	ds_read_b128 v[96:99], v197 offset:2304
	ds_read_b128 v[84:87], v197 offset:4608
	ds_read_b128 v[92:95], v197 offset:6912
	s_waitcnt lgkmcnt(3)
	v_mfma_f32_16x16x32_bf16 v[56:59], v[88:91], v[68:71], v[56:59]
	s_waitcnt lgkmcnt(2)
	v_mfma_f32_16x16x32_bf16 v[60:63], v[96:99], v[68:71], v[60:63]
	s_waitcnt lgkmcnt(1)
	v_mfma_f32_16x16x32_bf16 v[80:83], v[84:87], v[68:71], v[64:67]
	s_waitcnt lgkmcnt(0)
	v_mfma_f32_16x16x32_bf16 v[52:55], v[92:95], v[68:71], v[52:55]
	ds_read_b128 v[142:145], v194 offset:64
	ds_read_b128 v[68:71], v197 offset:64
	ds_read_b128 v[72:75], v197 offset:2368
	ds_read_b128 v[76:79], v197 offset:4672
	s_waitcnt lgkmcnt(2)
	v_mfma_f32_16x16x32_bf16 v[64:67], v[68:71], v[142:145], v[56:59]
	s_waitcnt lgkmcnt(0)
	v_mfma_f32_16x16x32_bf16 v[56:59], v[76:79], v[142:145], v[80:83]
	s_nop 2
	ds_read_b128 v[80:83], v197 offset:6976
	v_mfma_f32_16x16x32_bf16 v[60:63], v[72:75], v[142:145], v[60:63]
	s_waitcnt lgkmcnt(0)
	v_mfma_f32_16x16x32_bf16 v[52:55], v[80:83], v[142:145], v[52:55]
	v_mul_f32_e32 v142, v65, v65
	v_mul_f32_e32 v143, v67, v67
	v_fmac_f32_e32 v142, v64, v64
	v_fmac_f32_e32 v143, v66, v66
	v_add_f32_e32 v142, v142, v143
	s_nop 0
	v_mul_f32_e32 v143, v61, v61
	v_mul_f32_e32 v144, v63, v63
	v_fmac_f32_e32 v143, v60, v60
	v_fmac_f32_e32 v144, v62, v62
	v_add_f32_e32 v143, v143, v144
	v_add_f32_e32 v142, v142, v143
	v_mul_f32_e32 v143, v57, v57
	v_mul_f32_e32 v144, v59, v59
	v_fmac_f32_e32 v143, v56, v56
	v_fmac_f32_e32 v144, v58, v58
	v_add_f32_e32 v143, v143, v144
	v_add_f32_e32 v142, v142, v143
	v_mul_f32_e32 v143, v53, v53
	v_mul_f32_e32 v144, v55, v55
	v_fmac_f32_e32 v143, v52, v52
	v_fmac_f32_e32 v144, v54, v54
	v_add_f32_e32 v143, v143, v144
	v_and_b32_e32 v144, 64, v193
	v_add_f32_e32 v142, v142, v143
	v_xor_b32_e32 v143, 16, v193
	v_add_u32_e32 v144, 64, v144
	v_cmp_lt_i32_e32 vcc, v143, v144
	s_nop 1
	v_cndmask_b32_e32 v143, v193, v143, vcc
	v_lshlrev_b32_e32 v143, 2, v143
	ds_bpermute_b32 v143, v143, v142
	s_waitcnt lgkmcnt(0)
	v_add_f32_e32 v142, v142, v143
	v_xor_b32_e32 v143, 32, v193
	v_cmp_lt_i32_e32 vcc, v143, v144
	s_nop 1
	v_cndmask_b32_e32 v143, v193, v143, vcc
	v_lshlrev_b32_e32 v143, 2, v143
	ds_bpermute_b32 v143, v143, v142
	s_and_saveexec_b64 s[88:89], s[0:1]
	s_cbranch_execz .LBB0_378
	s_waitcnt lgkmcnt(0)
	v_add_f32_e32 v150, v142, v143
	v_add_u32_e32 v151, s56, v113
	ds_write_b32 v151, v150
.LBB0_378:
	s_or_b64 exec, exec, s[88:89]
	s_waitcnt lgkmcnt(0)
	s_add_i32 s57, s57, 64
	s_cmp_eq_u32 s33, s58
	v_pk_mul_f32 v[10:11], v[10:11], v[226:227]
	v_pk_mul_f32 v[8:9], v[8:9], v[224:225]
	v_pk_mul_f32 v[18:19], v[18:19], v[226:227]
	v_pk_mul_f32 v[16:17], v[16:17], v[224:225]
	v_pk_mul_f32 v[14:15], v[14:15], v[226:227]
	v_pk_mul_f32 v[12:13], v[12:13], v[224:225]
	v_pk_mul_f32 v[22:23], v[22:23], v[226:227]
	v_pk_mul_f32 v[20:21], v[20:21], v[224:225]
	v_pk_mul_f32 v[38:39], v[38:39], v[230:231]
	v_pk_mul_f32 v[36:37], v[36:37], v[228:229]
	v_pk_mul_f32 v[42:43], v[42:43], v[230:231]
	v_pk_mul_f32 v[40:41], v[40:41], v[228:229]
	v_pk_mul_f32 v[46:47], v[46:47], v[230:231]
	v_pk_mul_f32 v[44:45], v[44:45], v[228:229]
	v_pk_mul_f32 v[50:51], v[50:51], v[230:231]
	v_pk_mul_f32 v[48:49], v[48:49], v[228:229]
	s_nop 1
	v_mfma_f32_16x16x32_bf16 v[8:11], v[232:235], v[88:91], v[8:11]
	v_mfma_f32_16x16x32_bf16 v[12:15], v[232:235], v[84:87], v[12:15]
	v_mfma_f32_16x16x32_bf16 v[36:39], v[236:239], v[88:91], v[36:39]
	v_mfma_f32_16x16x32_bf16 v[44:47], v[236:239], v[84:87], v[44:47]
	v_mfma_f32_16x16x32_bf16 v[16:19], v[232:235], v[96:99], v[16:19]
	v_mfma_f32_16x16x32_bf16 v[20:23], v[232:235], v[92:95], v[20:23]
	v_mfma_f32_16x16x32_bf16 v[40:43], v[236:239], v[96:99], v[40:43]
	v_mfma_f32_16x16x32_bf16 v[48:51], v[236:239], v[92:95], v[48:51]
	v_mfma_f32_16x16x32_bf16 v[8:11], v[240:243], v[68:71], v[8:11]
	v_mfma_f32_16x16x32_bf16 v[16:19], v[240:243], v[72:75], v[16:19]
	v_mfma_f32_16x16x32_bf16 v[12:15], v[240:243], v[76:79], v[12:15]
	v_mfma_f32_16x16x32_bf16 v[20:23], v[240:243], v[80:83], v[20:23]
	v_mfma_f32_16x16x32_bf16 v[36:39], v[152:155], v[68:71], v[36:39]
	v_mfma_f32_16x16x32_bf16 v[40:43], v[152:155], v[72:75], v[40:43]
	v_mfma_f32_16x16x32_bf16 v[44:47], v[152:155], v[76:79], v[44:47]
	v_mfma_f32_16x16x32_bf16 v[48:51], v[152:155], v[80:83], v[48:51]
	s_cbranch_scc0 .LBB0_359
	s_waitcnt lgkmcnt(0)
	s_barrier
	s_and_b64 vcc, exec, s[74:75]
	s_mov_b32 s90, s51
	s_cbranch_vccz .LBB0_351
	v_add_u32_e32 v68, 0, v113
	v_add_u32_e32 v68, 0x21a00, v68
	ds_read_b64 v[68:69], v68
	s_waitcnt vmcnt(3)
	v_lshlrev_b32_e32 v71, 16, v128
	v_cmp_gt_u32_e32 vcc, s42, v111
	s_waitcnt lgkmcnt(0)
	v_add_f32_e32 v68, v68, v69
	v_fmamk_f32 v68, v68, 0x3c000000, v165
	v_mul_f32_e32 v69, 0x4b800000, v68
	v_cmp_gt_f32_e64 s[4:5], s93, v68
	s_nop 1
	v_cndmask_b32_e64 v68, v68, v69, s[4:5]
	v_rsq_f32_e32 v70, v68
	v_lshlrev_b64 v[68:69], 11, v[140:141]
	v_lshl_add_u64 v[68:69], s[60:61], 0, v[68:69]
	v_mul_f32_e32 v72, 0x45800000, v70
	v_cndmask_b32_e64 v70, v70, v72, s[4:5]
	v_mul_f32_e32 v64, v64, v70
	v_mul_f32_e32 v65, v65, v70
	v_mul_f32_e32 v32, v32, v64
	v_mul_f32_e32 v33, v33, v65
	v_and_b32_e32 v64, 0xffff0000, v128
	v_mul_f32_e32 v33, v33, v64
	v_mul_f32_e32 v64, v66, v70
	v_mul_f32_e32 v34, v34, v64
	v_lshlrev_b32_e32 v64, 16, v129
	v_mul_f32_e32 v34, v34, v64
	v_mul_f32_e32 v64, v67, v70
	v_mul_f32_e32 v32, v32, v71
	v_mul_f32_e32 v35, v35, v64
	v_and_b32_e32 v64, 0xffff0000, v129
	v_mul_f32_e32 v35, v35, v64
	v_cvt_pk_bf16_f32 v32, v32, v33
	v_cvt_pk_bf16_f32 v33, v34, v35
	v_mul_f32_e32 v34, v60, v70
	v_mul_f32_e32 v28, v28, v34
	s_waitcnt vmcnt(2)
	v_lshlrev_b32_e32 v34, 16, v138
	v_mul_f32_e32 v28, v28, v34
	v_mul_f32_e32 v34, v61, v70
	v_mul_f32_e32 v29, v29, v34
	v_and_b32_e32 v34, 0xffff0000, v138
	v_mul_f32_e32 v29, v29, v34
	v_mul_f32_e32 v34, v62, v70
	v_mul_f32_e32 v30, v30, v34
	v_lshlrev_b32_e32 v34, 16, v139
	v_mul_f32_e32 v30, v30, v34
	v_mul_f32_e32 v34, v63, v70
	v_mul_f32_e32 v31, v31, v34
	v_and_b32_e32 v34, 0xffff0000, v139
	v_mul_f32_e32 v31, v31, v34
	v_cvt_pk_bf16_f32 v34, v28, v29
	v_cvt_pk_bf16_f32 v35, v30, v31
	s_nop 0
	v_permlane16_swap_b32_e32 v32, v34
	v_permlane16_swap_b32_e32 v33, v35
	s_and_saveexec_b64 s[4:5], vcc
	s_cbranch_execz .LBB0_382
	v_lshl_add_u64 v[28:29], v[130:131], 1, v[68:69]
	global_store_dwordx4 v[28:29], v[32:35], off
